# stack15 + next-unit scalar block of F1a/F2a moved out of the unit-start path into the MFMA gaps of the peeled first K-tile (2 instrs behind each of 64 MFMAs; branch-free; temps renamed)
# speedup vs baseline: 1.0012x; 1.0012x over previous
; #define PG8_LDA(dst, b, h) do { _Pragma("unroll") for (int m = 0; m < 4; ++m) _Pragma("unroll") for (int k = 0; k < 2; ++k) dst[m][k] = *(const PG8_LAS bf16x8*)(lds + PG8_SA(b, h) + aoff + m * 2048 + k * 1024); } while (0)
;     __device__ __forceinline__ bool next(int i, Unit& u) const {
;         const long L = (long)i * G + c; if (L >= total) return false;
;         if (nM1 == 144 && nN1 == 8 && nM2 == 0 && G == 256) {
;             const int xcd = c & 7, o = c >> 3;
;             const int grp = (i < 4) ? xcd * 4 + i : 32 + (xcd >> 1), idx = (i < 4) ? o : (xcd & 1) * 16 + o;
;             u.pm = grp * 4 + (idx & 3); u.pn = idx >> 2; return true; }
;         int w = (int)L; { const int q = total / NXCD, r = total % NXCD, xcd = w % NXCD, off = w / NXCD; w = (xcd < r ? xcd * (q + 1) : r * (q + 1) + (xcd - r) * q) + off; }
;         int nM = nM1, nN = nN1; const bool second = w >= n1; if (second) { w -= n1; nM = nM2; nN = nN2; }
;         const int wgm = 4;
;         const int nig = wgm * nN, gid = w / nig, fm = gid * wgm, gsz = (nM - fm) < wgm ? (nM - fm) : wgm;
;         int pm = fm + ((w % nig) % gsz), pn = (w % nig) / gsz;
;         if (second) { pm += pm2; pn = pn < split ? a0 + pn : a1 + pn; }
;         u.pm = pm; u.pn = pn; return true;
; template <class Epi, class Sched, bool ALIGN_EPI = false, bool SP2 = false, bool ABLK = false, bool BBLK = false>
; __device__ __forceinline__ void gemm_phase(PG8_LAS unsigned char* lds, const Gemm g, const Sched& S, const Epi& E) {
;     ...
;         const char* nA = has_next ? (const char*)g.A + (size_t)nxt.pm * tstepA : cA; const char* nB = has_next ? (const char*)g.Bt + (size_t)nxt.pn * tstepB : cB;
;         for (int t = 0; t < nt; t += 2) {
;             const bool last = (t == nt - 2);
;             const char* a1 = cA + (size_t)(t + 1) * kstepA;
;             const char* a2 = last ? nA : cA + (size_t)(t + 2) * kstepA; const char* b2 = last ? nB : cB + (size_t)(t + 2) * kstepB;
;             const char* a3 = a2 + kstepA; const char* b3 = b2 + kstepB;
;             if (last && has_next) S.a_ready(nxt);
;             if constexpr (SP2) {
;             PG8_LDB(B0, 0, 0); PG8_LDB(B1, 0, 1); PG8_SCHED; PG8_LDA(At, 0, 0); PG8_STAGE(PG8_SA(1, 1), a1 + hstepA, voffA);
;             PG8_WAIT_V(8); PG8_WAIT_L(0); PG8_BAR; PG8_MMA(0, 0, At, B0); PG8_MMA(0, 1, At, B1); PG8_BAR; PG8_SCHED;
.LBB0_213:
	s_add_u32 s22, s22, 0xc000
	s_addc_u32 s23, s23, 0
	s_add_u32 s72, s24, 0x10000
	v_mov_b32_e32 v2, 0
	s_addc_u32 s73, s25, 0
	s_mov_b32 s81, -2
	s_add_u32 s24, s22, 0x4000
	s_addc_u32 s25, s23, 0
	s_cmp_eq_u32 s81, 28
	s_cselect_b32 s28, s65, s24
	s_cselect_b32 s29, s15, s25
	s_cselect_b32 s26, s68, s72
	s_cselect_b32 s27, s13, s73
	s_add_u32 s24, s28, 0x8000
	s_addc_u32 s25, s29, 0
	s_add_i32 s75, 0, 0x10000
	v_add_u32_e32 v142, s75, v145
	s_add_i32 s80, 0, 0x14000
	ds_read_b128 v[148:151], v142
	ds_read_b128 v[152:155], v142 offset:1024
	ds_read_b128 v[156:159], v142 offset:2048
	ds_read_b128 v[160:163], v142 offset:3072
	v_add_u32_e32 v142, s80, v145
	ds_read_b128 v[164:167], v142
	ds_read_b128 v[168:171], v142 offset:1024
	ds_read_b128 v[172:175], v142 offset:2048
	ds_read_b128 v[176:179], v142 offset:3072
	v_lshl_add_u64 v[142:143], s[22:23], 0, v[138:139]
	s_add_i32 m0, s43, 0xc000
	ds_read_b128 v[180:183], v146
	ds_read_b128 v[196:199], v146 offset:1024
	ds_read_b128 v[200:203], v146 offset:2048
	ds_read_b128 v[204:207], v146 offset:3072
	ds_read_b128 v[208:211], v146 offset:4096
	ds_read_b128 v[212:215], v146 offset:5120
	ds_read_b128 v[216:219], v146 offset:6144
	ds_read_b128 v[220:223], v146 offset:7168
	global_load_lds_dwordx4 v[142:143], off
	v_lshl_add_u64 v[142:143], s[22:23], 0, v[140:141]
	s_add_i32 m0, s43, 0xe000
	s_nop 0
	global_load_lds_dwordx4 v[142:143], off
	s_waitcnt vmcnt(8)
	s_waitcnt lgkmcnt(0)
	s_barrier
	s_setprio 1
	s_waitcnt lgkmcnt(0)
	v_mfma_f32_16x16x32_bf16 v[126:129], v[148:151], v[180:183], 0
	s_add_i32 s61, s61, 1
	s_mul_i32 s4, s61, s60
	v_mfma_f32_16x16x32_bf16 v[118:121], v[156:159], v[180:183], 0
	s_mul_hi_u32 s5, s61, s33
	s_add_i32 s5, s5, s4
	v_mfma_f32_16x16x32_bf16 v[110:113], v[148:151], v[200:203], 0
	s_mul_i32 s4, s61, s33
	s_add_u32 s18, s4, s34
	v_mfma_f32_16x16x32_bf16 v[102:105], v[156:159], v[200:203], 0
	s_addc_u32 s19, s5, s42
	v_mov_b64_e32 v[246:247], 0x18c0
	v_mfma_f32_16x16x32_bf16 v[94:97], v[148:151], v[208:211], 0
	v_cmp_lt_i64_e64 s[4:5], s[18:19], v[246:247]
	s_ashr_i32 s12, s18, 31
	v_mfma_f32_16x16x32_bf16 v[86:89], v[156:159], v[208:211], 0
	s_lshr_b32 s12, s12, 29
	s_add_i32 s12, s18, s12
	v_mfma_f32_16x16x32_bf16 v[78:81], v[148:151], v[216:219], 0
	s_ashr_i32 s13, s12, 3
	s_and_b32 s12, s12, -8
	v_mfma_f32_16x16x32_bf16 v[70:73], v[156:159], v[216:219], 0
	s_sub_i32 s12, s18, s12
	s_cmp_lt_i32 s12, 0
	v_mfma_f32_16x16x32_bf16 v[126:129], v[152:155], v[196:199], v[126:129]
	s_movk_i32 s14, 0x319
	s_cselect_b32 s14, s14, 0x318
	v_mfma_f32_16x16x32_bf16 v[118:121], v[160:163], v[196:199], v[118:121]
	s_mul_i32 s12, s12, s14
	s_add_i32 s12, s12, s13
	v_mfma_f32_16x16x32_bf16 v[110:113], v[152:155], v[204:207], v[110:113]
	s_cmpk_lt_i32 s12, 0x18c0
	s_cselect_b32 s13, 0xb0, 4
	v_mfma_f32_16x16x32_bf16 v[102:105], v[160:163], v[204:207], v[102:105]
	v_cvt_f32_ubyte0_e32 v246, s13
	v_rcp_iflag_f32_e32 v246, v246
	v_mfma_f32_16x16x32_bf16 v[94:97], v[152:155], v[212:215], v[94:97]
	s_cselect_b32 s14, 0, 0xffffe740
	s_cselect_b32 s15, 0x90, 0
	v_mfma_f32_16x16x32_bf16 v[86:89], v[160:163], v[212:215], v[86:89]
	s_sub_i32 s19, 0, s13
	v_mul_f32_e32 v246, 0x4f7ffffe, v246
	v_mfma_f32_16x16x32_bf16 v[78:81], v[152:155], v[220:223], v[78:81]
	v_cvt_u32_f32_e32 v246, v246
	s_add_i32 s14, s14, s12
	v_mfma_f32_16x16x32_bf16 v[70:73], v[160:163], v[220:223], v[70:73]
	s_abs_i32 s18, s14
	s_ashr_i32 s12, s14, 31
	s_setprio 0
	s_setprio 1
	v_mfma_f32_16x16x32_bf16 v[122:125], v[164:167], v[180:183], 0
	v_readfirstlane_b32 s20, v246
	s_mul_i32 s19, s19, s20
	v_mfma_f32_16x16x32_bf16 v[114:117], v[172:175], v[180:183], 0
	s_mul_hi_u32 s19, s20, s19
	s_add_i32 s20, s20, s19
	v_mfma_f32_16x16x32_bf16 v[106:109], v[164:167], v[200:203], 0
	s_mul_hi_u32 s19, s18, s20
	s_mul_i32 s20, s19, s13
	v_mfma_f32_16x16x32_bf16 v[98:101], v[172:175], v[200:203], 0
	s_sub_i32 s18, s18, s20
	s_add_i32 s20, s19, 1
	v_mfma_f32_16x16x32_bf16 v[90:93], v[164:167], v[208:211], 0
	s_sub_i32 s21, s18, s13
	s_cmp_ge_u32 s18, s13
	v_mfma_f32_16x16x32_bf16 v[82:85], v[172:175], v[208:211], 0
	s_cselect_b32 s19, s20, s19
	s_cselect_b32 s18, s21, s18
	v_mfma_f32_16x16x32_bf16 v[74:77], v[164:167], v[216:219], 0
	s_add_i32 s20, s19, 1
	s_cmp_ge_u32 s18, s13
	v_mfma_f32_16x16x32_bf16 v[66:69], v[172:175], v[216:219], 0
	s_cselect_b32 s18, s20, s19
	s_xor_b32 s18, s18, s12
	v_mfma_f32_16x16x32_bf16 v[122:125], v[168:171], v[196:199], v[122:125]
	s_sub_i32 s12, s18, s12
	s_lshl_b32 s18, s12, 2
	v_mfma_f32_16x16x32_bf16 v[114:117], v[176:179], v[196:199], v[114:117]
	s_sub_i32 s15, s15, s18
	s_min_i32 s15, s15, 4
	v_mfma_f32_16x16x32_bf16 v[106:109], v[168:171], v[204:207], v[106:109]
	s_abs_i32 s19, s15
	v_cvt_f32_u32_e32 v246, s19
	v_mfma_f32_16x16x32_bf16 v[98:101], v[176:179], v[204:207], v[98:101]
	s_sub_i32 s20, 0, s19
	s_mul_i32 s12, s12, s13
	v_mfma_f32_16x16x32_bf16 v[90:93], v[168:171], v[212:215], v[90:93]
	s_sub_i32 s13, s14, s12
	v_rcp_iflag_f32_e32 v246, v246
	v_mfma_f32_16x16x32_bf16 v[82:85], v[176:179], v[212:215], v[82:85]
	s_abs_i32 s12, s13
	s_xor_b32 s14, s13, s15
	v_mfma_f32_16x16x32_bf16 v[74:77], v[168:171], v[220:223], v[74:77]
	s_ashr_i32 s14, s14, 31
	v_mul_f32_e32 v246, 0x4f7ffffe, v246
	v_mfma_f32_16x16x32_bf16 v[66:69], v[176:179], v[220:223], v[66:69]
	v_cvt_u32_f32_e32 v246, v246
	s_nop 0
	s_setprio 0
	s_barrier
; #define PG8_STAGE(bufoff, gbase, voff) do { _Pragma("unroll") for (int _i = 0; _i < 2; ++_i) \
;         __builtin_amdgcn_global_load_lds((const unsigned*)((const char*)(gbase) + (voff)[_i]), (PG8_LAS unsigned*)(lds + (bufoff) + ldsw + _i * 8192), 16, 0, 0); } while (0)
; #define PG8_LDA(dst, b, h) do { _Pragma("unroll") for (int m = 0; m < 4; ++m) _Pragma("unroll") for (int k = 0; k < 2; ++k) dst[m][k] = *(const PG8_LAS bf16x8*)(lds + PG8_SA(b, h) + aoff + m * 2048 + k * 1024); } while (0)
; #define PG8_WAIT_V(n) asm volatile("s_waitcnt vmcnt(" #n ")" ::: "memory")
; #define PG8_WAIT_L(n) asm volatile("s_waitcnt lgkmcnt(" #n ")" ::: "memory")
; #define PG8_BAR __builtin_amdgcn_s_barrier()
; #define PG8_SCHED __builtin_amdgcn_sched_barrier(0)
;     __device__ __forceinline__ bool next(int i, Unit& u) const {
;         const long L = (long)i * G + c; if (L >= total) return false;
;         if (nM1 == 144 && nN1 == 8 && nM2 == 0 && G == 256) {
;             const int xcd = c & 7, o = c >> 3;
;             const int grp = (i < 4) ? xcd * 4 + i : 32 + (xcd >> 1), idx = (i < 4) ? o : (xcd & 1) * 16 + o;
;             u.pm = grp * 4 + (idx & 3); u.pn = idx >> 2; return true; }
;         int w = (int)L; { const int q = total / NXCD, r = total % NXCD, xcd = w % NXCD, off = w / NXCD; w = (xcd < r ? xcd * (q + 1) : r * (q + 1) + (xcd - r) * q) + off; }
;         int nM = nM1, nN = nN1; const bool second = w >= n1; if (second) { w -= n1; nM = nM2; nN = nN2; }
;         const int wgm = 4;
;         const int nig = wgm * nN, gid = w / nig, fm = gid * wgm, gsz = (nM - fm) < wgm ? (nM - fm) : wgm;
;         int pm = fm + ((w % nig) % gsz), pn = (w % nig) / gsz;
;         if (second) { pm += pm2; pn = pn < split ? a0 + pn : a1 + pn; }
;         u.pm = pm; u.pn = pn; return true;
; template <class Epi, class Sched, bool ALIGN_EPI = false, bool SP2 = false, bool ABLK = false, bool BBLK = false>
; __device__ __forceinline__ void gemm_phase(PG8_LAS unsigned char* lds, const Gemm g, const Sched& S, const Epi& E) {
;     ...
;             PG8_LDA(At, 0, 1); PG8_STAGE(PG8_SB(0, 0), b2, voffB); PG8_STAGE(PG8_SB(0, 1), b2 + hstepB, voffB); PG8_STAGE(PG8_SA(0, 0), a2, voffA);
;             PG8_WAIT_V(8); PG8_WAIT_L(0); PG8_BAR; PG8_MMA(1, 0, At, B0); PG8_MMA(1, 1, At, B1); PG8_BAR; PG8_SCHED;
	s_add_i32 s75, s75, s41
	v_lshl_add_u64 v[142:143], s[26:27], 0, v[134:135]
	s_mov_b32 m0, s75
	ds_read_b128 v[180:183], v146 offset:16384
	ds_read_b128 v[196:199], v146 offset:17408
	ds_read_b128 v[200:203], v146 offset:18432
	ds_read_b128 v[204:207], v146 offset:19456
	ds_read_b128 v[208:211], v146 offset:20480
	ds_read_b128 v[212:215], v146 offset:21504
	ds_read_b128 v[216:219], v146 offset:22528
	ds_read_b128 v[220:223], v146 offset:23552
	global_load_lds_dwordx4 v[142:143], off
	s_add_i32 m0, s75, 0x2000
	s_add_u32 s82, s26, 0x4000
	v_lshl_add_u64 v[142:143], s[26:27], 0, v[130:131]
	s_addc_u32 s83, s27, 0
	s_add_i32 s75, s80, s41
	global_load_lds_dwordx4 v[142:143], off
	v_lshl_add_u64 v[142:143], s[82:83], 0, v[134:135]
	s_mov_b32 m0, s75
	s_nop 0
	global_load_lds_dwordx4 v[142:143], off
	v_lshl_add_u64 v[142:143], s[82:83], 0, v[130:131]
	s_add_i32 m0, s75, 0x2000
	s_nop 0
	global_load_lds_dwordx4 v[142:143], off
	v_lshl_add_u64 v[142:143], s[28:29], 0, v[136:137]
	s_mov_b32 m0, s43
	s_nop 0
	global_load_lds_dwordx4 v[142:143], off
	v_lshl_add_u64 v[142:143], s[28:29], 0, v[132:133]
	s_mov_b32 m0, s44
	s_nop 0
	global_load_lds_dwordx4 v[142:143], off
	s_waitcnt vmcnt(8)
	s_waitcnt lgkmcnt(0)
	s_barrier
	s_setprio 1
	s_waitcnt lgkmcnt(0)
	v_mfma_f32_16x16x32_bf16 v[62:65], v[148:151], v[180:183], 0
	v_readfirstlane_b32 s21, v246
	s_mul_i32 s20, s20, s21
	v_mfma_f32_16x16x32_bf16 v[54:57], v[156:159], v[180:183], 0
	s_mul_hi_u32 s20, s21, s20
	s_add_i32 s21, s21, s20
	v_mfma_f32_16x16x32_bf16 v[46:49], v[148:151], v[200:203], 0
	s_mul_hi_u32 s20, s12, s21
	s_mul_i32 s21, s20, s19
	v_mfma_f32_16x16x32_bf16 v[38:41], v[156:159], v[200:203], 0
	s_sub_i32 s12, s12, s21
	s_add_i32 s21, s20, 1
	v_mfma_f32_16x16x32_bf16 v[30:33], v[148:151], v[208:211], 0
	s_sub_i32 s100, s12, s19
	s_cmp_ge_u32 s12, s19
	v_mfma_f32_16x16x32_bf16 v[22:25], v[156:159], v[208:211], 0
	s_cselect_b32 s20, s21, s20
	s_cselect_b32 s12, s100, s12
	v_mfma_f32_16x16x32_bf16 v[14:17], v[148:151], v[216:219], 0
	s_add_i32 s21, s20, 1
	s_cmp_ge_u32 s12, s19
	v_mfma_f32_16x16x32_bf16 v[6:9], v[156:159], v[216:219], 0
	s_cselect_b32 s12, s21, s20
	s_xor_b32 s12, s12, s14
	v_mfma_f32_16x16x32_bf16 v[62:65], v[152:155], v[196:199], v[62:65]
	s_sub_i32 s12, s12, s14
	s_mul_i32 s14, s12, s15
	v_mfma_f32_16x16x32_bf16 v[54:57], v[160:163], v[196:199], v[54:57]
	s_sub_i32 s13, s13, s14
	s_add_i32 s14, s13, s18
	v_mfma_f32_16x16x32_bf16 v[46:49], v[152:155], v[204:207], v[46:49]
	s_ashr_i32 s15, s14, 31
	s_lshl_b64 s[18:19], s[14:15], 20
	v_mfma_f32_16x16x32_bf16 v[38:41], v[160:163], v[204:207], v[38:41]
	s_add_u32 s18, s35, s18
	s_addc_u32 s19, s36, s19
	v_mfma_f32_16x16x32_bf16 v[30:33], v[152:155], v[212:215], v[30:33]
	s_and_b64 s[20:21], s[4:5], exec
	s_cselect_b32 s15, s19, s23
	v_mfma_f32_16x16x32_bf16 v[22:25], v[160:163], v[212:215], v[22:25]
	s_cselect_b32 s65, s18, s22
	s_ashr_i32 s13, s12, 31
	v_mfma_f32_16x16x32_bf16 v[14:17], v[152:155], v[220:223], v[14:17]
	s_lshl_b64 s[20:21], s[12:13], 20
	s_add_u32 s20, s37, s20
	v_mfma_f32_16x16x32_bf16 v[6:9], v[160:163], v[220:223], v[6:9]
	s_addc_u32 s21, s40, s21
	s_and_b64 s[100:101], s[4:5], exec
	s_setprio 0
	s_setprio 1
	v_mfma_f32_16x16x32_bf16 v[58:61], v[164:167], v[180:183], 0
	s_cselect_b32 s13, s21, s25
	s_cselect_b32 s68, s20, s24
	v_mfma_f32_16x16x32_bf16 v[50:53], v[172:175], v[180:183], 0
	v_mfma_f32_16x16x32_bf16 v[42:45], v[164:167], v[200:203], 0
	v_mfma_f32_16x16x32_bf16 v[34:37], v[172:175], v[200:203], 0
	v_mfma_f32_16x16x32_bf16 v[26:29], v[164:167], v[208:211], 0
	v_mfma_f32_16x16x32_bf16 v[18:21], v[172:175], v[208:211], 0
	v_mfma_f32_16x16x32_bf16 v[10:13], v[164:167], v[216:219], 0
	v_mfma_f32_16x16x32_bf16 v[2:5], v[172:175], v[216:219], 0
	v_mfma_f32_16x16x32_bf16 v[58:61], v[168:171], v[196:199], v[58:61]
	v_mfma_f32_16x16x32_bf16 v[50:53], v[176:179], v[196:199], v[50:53]
	v_mfma_f32_16x16x32_bf16 v[42:45], v[168:171], v[204:207], v[42:45]
	v_mfma_f32_16x16x32_bf16 v[34:37], v[176:179], v[204:207], v[34:37]
	v_mfma_f32_16x16x32_bf16 v[26:29], v[168:171], v[212:215], v[26:29]
	v_mfma_f32_16x16x32_bf16 v[18:21], v[176:179], v[212:215], v[18:21]
	v_mfma_f32_16x16x32_bf16 v[10:13], v[168:171], v[220:223], v[10:13]
	v_mfma_f32_16x16x32_bf16 v[2:5], v[176:179], v[220:223], v[2:5]
	s_setprio 0
	s_barrier
	s_branch .Lmid_216

; #define PG8_LDA(dst, b, h) do { _Pragma("unroll") for (int m = 0; m < 4; ++m) _Pragma("unroll") for (int k = 0; k < 2; ++k) dst[m][k] = *(const PG8_LAS bf16x8*)(lds + PG8_SA(b, h) + aoff + m * 2048 + k * 1024); } while (0)
;     __device__ __forceinline__ bool next(int i, Unit& u) const {
;         const long L = (long)i * G + c; if (L >= total) return false;
;         if (nM1 == 144 && nN1 == 8 && nM2 == 0 && G == 256) {
;             const int xcd = c & 7, o = c >> 3;
;             const int grp = (i < 4) ? xcd * 4 + i : 32 + (xcd >> 1), idx = (i < 4) ? o : (xcd & 1) * 16 + o;
;             u.pm = grp * 4 + (idx & 3); u.pn = idx >> 2; return true; }
;         int w = (int)L; { const int q = total / NXCD, r = total % NXCD, xcd = w % NXCD, off = w / NXCD; w = (xcd < r ? xcd * (q + 1) : r * (q + 1) + (xcd - r) * q) + off; }
;         int nM = nM1, nN = nN1; const bool second = w >= n1; if (second) { w -= n1; nM = nM2; nN = nN2; }
;         const int wgm = 4;
;         const int nig = wgm * nN, gid = w / nig, fm = gid * wgm, gsz = (nM - fm) < wgm ? (nM - fm) : wgm;
;         int pm = fm + ((w % nig) % gsz), pn = (w % nig) / gsz;
;         if (second) { pm += pm2; pn = pn < split ? a0 + pn : a1 + pn; }
;         u.pm = pm; u.pn = pn; return true;
; template <class Epi, class Sched, bool ALIGN_EPI = false, bool SP2 = false, bool ABLK = false, bool BBLK = false>
; __device__ __forceinline__ void gemm_phase(PG8_LAS unsigned char* lds, const Gemm g, const Sched& S, const Epi& E) {
;     ...
;         const char* nA = has_next ? (const char*)g.A + (size_t)nxt.pm * tstepA : cA; const char* nB = has_next ? (const char*)g.Bt + (size_t)nxt.pn * tstepB : cB;
;         for (int t = 0; t < nt; t += 2) {
;             const bool last = (t == nt - 2);
;             const char* a1 = cA + (size_t)(t + 1) * kstepA;
;             const char* a2 = last ? nA : cA + (size_t)(t + 2) * kstepA; const char* b2 = last ? nB : cB + (size_t)(t + 2) * kstepB;
;             const char* a3 = a2 + kstepA; const char* b3 = b2 + kstepB;
;             if (last && has_next) S.a_ready(nxt);
;             if constexpr (SP2) {
;             PG8_LDB(B0, 0, 0); PG8_LDB(B1, 0, 1); PG8_SCHED; PG8_LDA(At, 0, 0); PG8_STAGE(PG8_SA(1, 1), a1 + hstepA, voffA);
;             PG8_WAIT_V(8); PG8_WAIT_L(0); PG8_BAR; PG8_MMA(0, 0, At, B0); PG8_MMA(0, 1, At, B1); PG8_BAR; PG8_SCHED;
.LBB0_1337:
	s_add_u32 s26, s26, 0xc000
	s_addc_u32 s27, s27, 0
	s_add_u32 s73, s28, 0x10000
	v_mov_b32_e32 v2, 0
	s_addc_u32 s81, s29, 0
	s_mov_b32 s83, -2
	s_add_u32 s28, s26, 0x4000
	s_addc_u32 s29, s27, 0
	s_cmp_eq_u32 s83, 28
	s_cselect_b32 s34, s19, s28
	s_cselect_b32 s35, s1, s29
	s_cselect_b32 s30, s72, s73
	s_cselect_b32 s31, s15, s81
	s_add_u32 s28, s34, 0x8000
	s_addc_u32 s29, s35, 0
	s_add_i32 s52, 0, 0x10000
	v_add_u32_e32 v142, s52, v145
	s_add_i32 s75, 0, 0x14000
	ds_read_b128 v[148:151], v142
	ds_read_b128 v[152:155], v142 offset:1024
	ds_read_b128 v[156:159], v142 offset:2048
	ds_read_b128 v[160:163], v142 offset:3072
	v_add_u32_e32 v142, s75, v145
	ds_read_b128 v[164:167], v142
	ds_read_b128 v[168:171], v142 offset:1024
	ds_read_b128 v[172:175], v142 offset:2048
	ds_read_b128 v[176:179], v142 offset:3072
	v_lshl_add_u64 v[142:143], s[26:27], 0, v[138:139]
	s_add_i32 m0, s25, 0xc000
	ds_read_b128 v[180:183], v146
	ds_read_b128 v[196:199], v146 offset:1024
	ds_read_b128 v[200:203], v146 offset:2048
	ds_read_b128 v[204:207], v146 offset:3072
	ds_read_b128 v[208:211], v146 offset:4096
	ds_read_b128 v[212:215], v146 offset:5120
	ds_read_b128 v[216:219], v146 offset:6144
	ds_read_b128 v[220:223], v146 offset:7168
	global_load_lds_dwordx4 v[142:143], off
	v_lshl_add_u64 v[142:143], s[26:27], 0, v[140:141]
	s_add_i32 m0, s25, 0xe000
	s_nop 0
	global_load_lds_dwordx4 v[142:143], off
	s_waitcnt vmcnt(8)
	s_waitcnt lgkmcnt(0)
	s_barrier
	s_setprio 1
	s_waitcnt lgkmcnt(0)
	v_mfma_f32_16x16x32_bf16 v[126:129], v[148:151], v[180:183], 0
	s_add_i32 s68, s68, 1
	s_mul_i32 s1, s68, s65
	v_mfma_f32_16x16x32_bf16 v[118:121], v[156:159], v[180:183], 0
	s_mul_hi_u32 s6, s68, s33
	s_add_i32 s6, s6, s1
	v_mfma_f32_16x16x32_bf16 v[110:113], v[148:151], v[200:203], 0
	s_mul_i32 s1, s68, s33
	s_add_u32 s20, s1, s36
	v_mfma_f32_16x16x32_bf16 v[102:105], v[156:159], v[200:203], 0
	s_addc_u32 s21, s6, s45
	v_mov_b64_e32 v[246:247], s[2:3]
	v_mfma_f32_16x16x32_bf16 v[94:97], v[148:151], v[208:211], 0
	v_cmp_lt_i64_e64 s[6:7], s[20:21], v[246:247]
	s_ashr_i32 s1, s20, 31
	v_mfma_f32_16x16x32_bf16 v[86:89], v[156:159], v[208:211], 0
	s_lshr_b32 s1, s1, 29
	s_add_i32 s1, s20, s1
	v_mfma_f32_16x16x32_bf16 v[78:81], v[148:151], v[216:219], 0
	s_ashr_i32 s14, s1, 3
	s_and_b32 s1, s1, -8
	v_mfma_f32_16x16x32_bf16 v[70:73], v[156:159], v[216:219], 0
	s_sub_i32 s1, s20, s1
	s_lshr_b32 s15, s1, 31
	v_mfma_f32_16x16x32_bf16 v[126:129], v[152:155], v[196:199], v[126:129]
	s_or_b32 s15, s37, s15
	s_mul_i32 s1, s15, s1
	v_mfma_f32_16x16x32_bf16 v[118:121], v[160:163], v[196:199], v[118:121]
	s_add_i32 s1, s1, s14
	s_cmp_lt_i32 s1, s2
	v_mfma_f32_16x16x32_bf16 v[110:113], v[152:155], v[204:207], v[110:113]
	s_cselect_b32 s14, 0xb0, 4
	v_cvt_f32_ubyte0_e32 v246, s14
	v_mfma_f32_16x16x32_bf16 v[102:105], v[160:163], v[204:207], v[102:105]
	v_rcp_iflag_f32_e32 v246, v246
	v_readlane_b32 s18, v254, 32
	v_mfma_f32_16x16x32_bf16 v[94:97], v[152:155], v[212:215], v[94:97]
	s_cselect_b32 s15, 0, s2
	s_cselect_b32 s18, s18, 0
	v_mfma_f32_16x16x32_bf16 v[86:89], v[160:163], v[212:215], v[86:89]
	v_mul_f32_e32 v246, 0x4f7ffffe, v246
	v_cvt_u32_f32_e32 v246, v246
	v_mfma_f32_16x16x32_bf16 v[78:81], v[152:155], v[220:223], v[78:81]
	s_sub_i32 s20, 0, s14
	s_sub_i32 s1, s1, s15
	v_mfma_f32_16x16x32_bf16 v[70:73], v[160:163], v[220:223], v[70:73]
	s_abs_i32 s19, s1
	v_readfirstlane_b32 s21, v246
	s_setprio 0
	s_setprio 1
	v_mfma_f32_16x16x32_bf16 v[122:125], v[164:167], v[180:183], 0
	s_mul_i32 s20, s20, s21
	s_mul_hi_u32 s20, s21, s20
	v_mfma_f32_16x16x32_bf16 v[114:117], v[172:175], v[180:183], 0
	s_add_i32 s21, s21, s20
	s_mul_hi_u32 s20, s19, s21
	v_mfma_f32_16x16x32_bf16 v[106:109], v[164:167], v[200:203], 0
	s_mul_i32 s21, s20, s14
	s_sub_i32 s19, s19, s21
	v_mfma_f32_16x16x32_bf16 v[98:101], v[172:175], v[200:203], 0
	s_ashr_i32 s15, s1, 31
	s_add_i32 s21, s20, 1
	v_mfma_f32_16x16x32_bf16 v[90:93], v[164:167], v[208:211], 0
	s_sub_i32 s22, s19, s14
	s_cmp_ge_u32 s19, s14
	v_mfma_f32_16x16x32_bf16 v[82:85], v[172:175], v[208:211], 0
	s_cselect_b32 s20, s21, s20
	s_cselect_b32 s19, s22, s19
	v_mfma_f32_16x16x32_bf16 v[74:77], v[164:167], v[216:219], 0
	s_add_i32 s21, s20, 1
	s_cmp_ge_u32 s19, s14
	v_mfma_f32_16x16x32_bf16 v[66:69], v[172:175], v[216:219], 0
	s_cselect_b32 s19, s21, s20
	s_xor_b32 s19, s19, s15
	v_mfma_f32_16x16x32_bf16 v[122:125], v[168:171], v[196:199], v[122:125]
	s_sub_i32 s15, s19, s15
	s_lshl_b32 s19, s15, 2
	v_mfma_f32_16x16x32_bf16 v[114:117], v[176:179], v[196:199], v[114:117]
	s_sub_i32 s18, s18, s19
	s_min_i32 s18, s18, 4
	v_mfma_f32_16x16x32_bf16 v[106:109], v[168:171], v[204:207], v[106:109]
	s_abs_i32 s20, s18
	v_cvt_f32_u32_e32 v246, s20
	v_mfma_f32_16x16x32_bf16 v[98:101], v[176:179], v[204:207], v[98:101]
	s_sub_i32 s21, 0, s20
	s_mul_i32 s15, s15, s14
	v_mfma_f32_16x16x32_bf16 v[90:93], v[168:171], v[212:215], v[90:93]
	s_sub_i32 s1, s1, s15
	v_rcp_iflag_f32_e32 v246, v246
	v_mfma_f32_16x16x32_bf16 v[82:85], v[176:179], v[212:215], v[82:85]
	s_abs_i32 s14, s1
	s_xor_b32 s15, s1, s18
	v_mfma_f32_16x16x32_bf16 v[74:77], v[168:171], v[220:223], v[74:77]
	s_ashr_i32 s15, s15, 31
	v_mul_f32_e32 v246, 0x4f7ffffe, v246
	v_mfma_f32_16x16x32_bf16 v[66:69], v[176:179], v[220:223], v[66:69]
	v_cvt_u32_f32_e32 v246, v246
	s_nop 0
	s_setprio 0
	s_barrier
; #define PG8_STAGE(bufoff, gbase, voff) do { _Pragma("unroll") for (int _i = 0; _i < 2; ++_i) \
;         __builtin_amdgcn_global_load_lds((const unsigned*)((const char*)(gbase) + (voff)[_i]), (PG8_LAS unsigned*)(lds + (bufoff) + ldsw + _i * 8192), 16, 0, 0); } while (0)
; #define PG8_LDA(dst, b, h) do { _Pragma("unroll") for (int m = 0; m < 4; ++m) _Pragma("unroll") for (int k = 0; k < 2; ++k) dst[m][k] = *(const PG8_LAS bf16x8*)(lds + PG8_SA(b, h) + aoff + m * 2048 + k * 1024); } while (0)
; #define PG8_WAIT_V(n) asm volatile("s_waitcnt vmcnt(" #n ")" ::: "memory")
; #define PG8_WAIT_L(n) asm volatile("s_waitcnt lgkmcnt(" #n ")" ::: "memory")
; #define PG8_BAR __builtin_amdgcn_s_barrier()
; #define PG8_SCHED __builtin_amdgcn_sched_barrier(0)
;     __device__ __forceinline__ bool next(int i, Unit& u) const {
;         const long L = (long)i * G + c; if (L >= total) return false;
;         if (nM1 == 144 && nN1 == 8 && nM2 == 0 && G == 256) {
;             const int xcd = c & 7, o = c >> 3;
;             const int grp = (i < 4) ? xcd * 4 + i : 32 + (xcd >> 1), idx = (i < 4) ? o : (xcd & 1) * 16 + o;
;             u.pm = grp * 4 + (idx & 3); u.pn = idx >> 2; return true; }
;         int w = (int)L; { const int q = total / NXCD, r = total % NXCD, xcd = w % NXCD, off = w / NXCD; w = (xcd < r ? xcd * (q + 1) : r * (q + 1) + (xcd - r) * q) + off; }
;         int nM = nM1, nN = nN1; const bool second = w >= n1; if (second) { w -= n1; nM = nM2; nN = nN2; }
;         const int wgm = 4;
;         const int nig = wgm * nN, gid = w / nig, fm = gid * wgm, gsz = (nM - fm) < wgm ? (nM - fm) : wgm;
;         int pm = fm + ((w % nig) % gsz), pn = (w % nig) / gsz;
;         if (second) { pm += pm2; pn = pn < split ? a0 + pn : a1 + pn; }
;         u.pm = pm; u.pn = pn; return true;
; template <class Epi, class Sched, bool ALIGN_EPI = false, bool SP2 = false, bool ABLK = false, bool BBLK = false>
; __device__ __forceinline__ void gemm_phase(PG8_LAS unsigned char* lds, const Gemm g, const Sched& S, const Epi& E) {
;     ...
;             PG8_LDA(At, 0, 1); PG8_STAGE(PG8_SB(0, 0), b2, voffB); PG8_STAGE(PG8_SB(0, 1), b2 + hstepB, voffB); PG8_STAGE(PG8_SA(0, 0), a2, voffA);
;             PG8_WAIT_V(8); PG8_WAIT_L(0); PG8_BAR; PG8_MMA(1, 0, At, B0); PG8_MMA(1, 1, At, B1); PG8_BAR; PG8_SCHED;
	s_add_i32 s52, s52, s44
	v_lshl_add_u64 v[142:143], s[30:31], 0, v[134:135]
	s_mov_b32 m0, s52
	ds_read_b128 v[180:183], v146 offset:16384
	ds_read_b128 v[196:199], v146 offset:17408
	ds_read_b128 v[200:203], v146 offset:18432
	ds_read_b128 v[204:207], v146 offset:19456
	ds_read_b128 v[208:211], v146 offset:20480
	ds_read_b128 v[212:215], v146 offset:21504
	ds_read_b128 v[216:219], v146 offset:22528
	ds_read_b128 v[220:223], v146 offset:23552
	global_load_lds_dwordx4 v[142:143], off
	s_add_i32 m0, s52, 0x2000
	s_add_u32 s88, s30, 0x4000
	v_lshl_add_u64 v[142:143], s[30:31], 0, v[130:131]
	s_addc_u32 s89, s31, 0
	s_add_i32 s52, s75, s44
	global_load_lds_dwordx4 v[142:143], off
	v_lshl_add_u64 v[142:143], s[88:89], 0, v[134:135]
	s_mov_b32 m0, s52
	s_nop 0
	global_load_lds_dwordx4 v[142:143], off
	v_lshl_add_u64 v[142:143], s[88:89], 0, v[130:131]
	s_add_i32 m0, s52, 0x2000
	s_nop 0
	global_load_lds_dwordx4 v[142:143], off
	v_lshl_add_u64 v[142:143], s[34:35], 0, v[136:137]
	s_mov_b32 m0, s25
	s_nop 0
	global_load_lds_dwordx4 v[142:143], off
	v_lshl_add_u64 v[142:143], s[34:35], 0, v[132:133]
	s_mov_b32 m0, s46
	s_nop 0
	global_load_lds_dwordx4 v[142:143], off
	s_waitcnt vmcnt(8)
	s_waitcnt lgkmcnt(0)
	s_barrier
	s_setprio 1
	s_waitcnt lgkmcnt(0)
	v_mfma_f32_16x16x32_bf16 v[62:65], v[148:151], v[180:183], 0
	v_readfirstlane_b32 s22, v246
	s_mul_i32 s21, s21, s22
	v_mfma_f32_16x16x32_bf16 v[54:57], v[156:159], v[180:183], 0
	s_mul_hi_u32 s21, s22, s21
	s_add_i32 s22, s22, s21
	v_mfma_f32_16x16x32_bf16 v[46:49], v[148:151], v[200:203], 0
	s_mul_hi_u32 s21, s14, s22
	s_mul_i32 s22, s21, s20
	v_mfma_f32_16x16x32_bf16 v[38:41], v[156:159], v[200:203], 0
	s_sub_i32 s14, s14, s22
	s_add_i32 s22, s21, 1
	v_mfma_f32_16x16x32_bf16 v[30:33], v[148:151], v[208:211], 0
	s_sub_i32 s23, s14, s20
	s_cmp_ge_u32 s14, s20
	v_mfma_f32_16x16x32_bf16 v[22:25], v[156:159], v[208:211], 0
	s_cselect_b32 s21, s22, s21
	s_cselect_b32 s14, s23, s14
	v_mfma_f32_16x16x32_bf16 v[14:17], v[148:151], v[216:219], 0
	s_add_i32 s22, s21, 1
	s_cmp_ge_u32 s14, s20
	v_mfma_f32_16x16x32_bf16 v[6:9], v[156:159], v[216:219], 0
	s_cselect_b32 s14, s22, s21
	s_xor_b32 s14, s14, s15
	v_mfma_f32_16x16x32_bf16 v[62:65], v[152:155], v[196:199], v[62:65]
	s_sub_i32 s14, s14, s15
	s_mul_i32 s15, s14, s18
	v_mfma_f32_16x16x32_bf16 v[54:57], v[160:163], v[196:199], v[54:57]
	s_sub_i32 s1, s1, s15
	s_add_i32 s18, s1, s19
	v_mfma_f32_16x16x32_bf16 v[46:49], v[152:155], v[204:207], v[46:49]
	s_ashr_i32 s19, s18, 31
	s_lshl_b64 s[20:21], s[18:19], 20
	v_mfma_f32_16x16x32_bf16 v[38:41], v[160:163], v[204:207], v[38:41]
	s_add_u32 s20, s40, s20
	s_addc_u32 s21, s41, s21
	v_mfma_f32_16x16x32_bf16 v[30:33], v[152:155], v[212:215], v[30:33]
	s_and_b64 s[22:23], s[6:7], exec
	s_cselect_b32 s1, s21, s27
	v_mfma_f32_16x16x32_bf16 v[22:25], v[160:163], v[212:215], v[22:25]
	s_cselect_b32 s19, s20, s26
	s_ashr_i32 s15, s14, 31
	v_mfma_f32_16x16x32_bf16 v[14:17], v[152:155], v[220:223], v[14:17]
	s_lshl_b64 s[22:23], s[14:15], 20
	s_add_u32 s22, s42, s22
	v_mfma_f32_16x16x32_bf16 v[6:9], v[160:163], v[220:223], v[6:9]
	s_addc_u32 s23, s43, s23
	s_and_b64 s[100:101], s[6:7], exec
	s_setprio 0
	s_setprio 1
	v_mfma_f32_16x16x32_bf16 v[58:61], v[164:167], v[180:183], 0
	s_cselect_b32 s15, s23, s29
	s_cselect_b32 s72, s22, s28
	v_mfma_f32_16x16x32_bf16 v[50:53], v[172:175], v[180:183], 0
	v_mfma_f32_16x16x32_bf16 v[42:45], v[164:167], v[200:203], 0
	v_mfma_f32_16x16x32_bf16 v[34:37], v[172:175], v[200:203], 0
	v_mfma_f32_16x16x32_bf16 v[26:29], v[164:167], v[208:211], 0
	v_mfma_f32_16x16x32_bf16 v[18:21], v[172:175], v[208:211], 0
	v_mfma_f32_16x16x32_bf16 v[10:13], v[164:167], v[216:219], 0
	v_mfma_f32_16x16x32_bf16 v[2:5], v[172:175], v[216:219], 0
	v_mfma_f32_16x16x32_bf16 v[58:61], v[168:171], v[196:199], v[58:61]
	v_mfma_f32_16x16x32_bf16 v[50:53], v[176:179], v[196:199], v[50:53]
	v_mfma_f32_16x16x32_bf16 v[42:45], v[168:171], v[204:207], v[42:45]
	v_mfma_f32_16x16x32_bf16 v[34:37], v[176:179], v[204:207], v[34:37]
	v_mfma_f32_16x16x32_bf16 v[26:29], v[168:171], v[212:215], v[26:29]
	v_mfma_f32_16x16x32_bf16 v[18:21], v[176:179], v[212:215], v[18:21]
	v_mfma_f32_16x16x32_bf16 v[10:13], v[168:171], v[220:223], v[10:13]
	v_mfma_f32_16x16x32_bf16 v[2:5], v[176:179], v[220:223], v[2:5]
	s_setprio 0
	s_barrier
	s_branch .Lmid_1340
